# NORM sample-row tail: the two remaining ds_bpermute wave reductions as DPP butterflies; NORM mid-compute param waits made unconditional (robustness)
# speedup vs baseline: 1.0008x; 1.0008x over previous
; __device__ __forceinline__ void norm_phase(const Ctx& c, int s) {
;     ...
;                 float ss = 0.f;
; #pragma unroll
;                 for (int j = 0; j < 4; ++j) ss += (fv[j][0] * fv[j][0] + fv[j][1] * fv[j][1]) + (fv[j][2] * fv[j][2] + fv[j][3] * fv[j][3]);
;                 rf = rsqrtf(wave_sum(ss) * (1.0f / D) + EPS);
;             }
;             NORM_PARAMS(8 + (rs >> 3));
.LBB0_809:
	v_pk_mul_f32 v[0:1], v[82:83], v[82:83]
	v_pk_mul_f32 v[84:85], v[80:81], v[80:81]
	v_mul_f32_e32 v3, v68, v68
	v_pk_mov_b32 v[86:87], v[84:85], v[0:1] op_sel:[1,0]
	v_mov_b32_e32 v85, v1
	v_pk_add_f32 v[0:1], v[86:87], v[84:85]
	v_pk_mul_f32 v[84:85], v[78:79], v[78:79]
	v_pk_mul_f32 v[86:87], v[76:77], v[76:77]
	v_pk_add_f32 v[0:1], v[0:1], v[0:1] op_sel:[0,1] op_sel_hi:[1,0]
	v_pk_mov_b32 v[88:89], v[86:87], v[84:85] op_sel:[1,0]
	v_mov_b32_e32 v87, v85
	v_pk_add_f32 v[84:85], v[88:89], v[86:87]
	v_mul_f32_e32 v86, v69, v69
	v_pk_add_f32 v[84:85], v[84:85], v[84:85] op_sel:[0,1] op_sel_hi:[1,0]
	v_mov_b32_e32 v1, v3
	v_mov_b32_e32 v85, v86
	v_pk_add_f32 v[0:1], v[0:1], v[84:85]
	v_mul_f32_e32 v84, v73, v73
	v_mul_f32_e32 v87, v70, v70
	v_pk_fma_f32 v[84:85], v[72:73], v[72:73], v[84:85] op_sel_hi:[1,1,0]
	v_mul_f32_e32 v86, v75, v75
	v_mul_f32_e32 v88, v71, v71
	v_mov_b32_e32 v85, v87
	v_pk_fma_f32 v[86:87], v[74:75], v[74:75], v[86:87] op_sel_hi:[1,1,0]
	v_xor_b32_e32 v3, 1, v234
	v_mov_b32_e32 v87, v88
	v_pk_add_f32 v[84:85], v[84:85], v[86:87]
	s_nop 0
	v_pk_add_f32 v[0:1], v[0:1], v[84:85]
	s_nop 0
	v_add_f32_e32 v0, v0, v1
	s_nop 1
	v_add_f32_dpp v0, v0, v0 quad_perm:[1,0,3,2] row_mask:0xf bank_mask:0xf
	s_nop 1
	v_add_f32_dpp v0, v0, v0 quad_perm:[2,3,0,1] row_mask:0xf bank_mask:0xf
	s_nop 1
	v_add_f32_dpp v0, v0, v0 row_half_mirror row_mask:0xf bank_mask:0xf
	s_nop 1
	v_add_f32_dpp v0, v0, v0 row_mirror row_mask:0xf bank_mask:0xf
	s_nop 1
	v_add_f32_dpp v0, v0, v0 row_bcast:15 row_mask:0xa bank_mask:0xf
	s_nop 1
	v_add_f32_dpp v0, v0, v0 row_bcast:31 row_mask:0xc bank_mask:0xf
	s_nop 0
	v_readlane_b32 s32, v0, 63
	s_nop 1
	v_mov_b32_e32 v0, s32
	s_waitcnt lgkmcnt(0)
	v_fmamk_f32 v0, v0, 0x3a800000, v228
	v_mul_f32_e32 v1, 0x4b800000, v0
	v_cmp_gt_f32_e32 vcc, s37, v0
	s_nop 1
	v_cndmask_b32_e32 v0, v0, v1, vcc
	v_rsq_f32_e32 v0, v0
	s_nop 0
	v_mul_f32_e32 v1, 0x45800000, v0
	v_cndmask_b32_e32 v0, v0, v1, vcc
	s_ashr_i32 s15, s14, 3
	s_add_i32 s15, s15, 8
	s_cmp_eq_u32 s15, s51
	s_cbranch_scc0 .LBB0_749

.LBB0_827:
	s_and_b64 vcc, exec, s[2:3]
	s_cbranch_vccnz .LBB0_742
	s_waitcnt vmcnt(3)
	v_pk_mul_f32 v[0:1], v[66:67], v[66:67]
	v_pk_mul_f32 v[68:69], v[64:65], v[64:65]
	v_xor_b32_e32 v3, 1, v234
	v_pk_mov_b32 v[70:71], v[68:69], v[0:1] op_sel:[1,0]
	v_mov_b32_e32 v69, v1
	v_pk_add_f32 v[0:1], v[70:71], v[68:69]
	s_waitcnt vmcnt(2)
	v_pk_mul_f32 v[68:69], v[62:63], v[62:63]
	v_pk_add_f32 v[0:1], v[0:1], v[0:1] op_sel_hi:[0,1]
	v_pk_mul_f32 v[70:71], v[60:61], v[60:61]
	s_waitcnt vmcnt(1)
	v_mul_f32_e32 v0, v56, v56
	v_pk_mov_b32 v[72:73], v[70:71], v[68:69] op_sel:[1,0]
	v_mov_b32_e32 v71, v69
	v_pk_add_f32 v[68:69], v[72:73], v[70:71]
	v_pk_fma_f32 v[70:71], v[56:57], v[56:57], v[0:1] op_sel_hi:[1,1,0]
	v_mul_f32_e32 v0, v58, v58
	v_pk_add_f32 v[68:69], v[68:69], v[68:69] op_sel_hi:[0,1]
	v_pk_fma_f32 v[72:73], v[58:59], v[58:59], v[0:1] op_sel_hi:[1,1,0]
	s_waitcnt vmcnt(0)
	v_mul_f32_e32 v70, v52, v52
	v_mul_f32_e32 v72, v53, v53
	v_mul_f32_e32 v68, v54, v54
	v_mul_f32_e32 v0, v55, v55
	v_pk_add_f32 v[70:71], v[70:71], v[72:73]
	v_pk_add_f32 v[0:1], v[68:69], v[0:1]
	s_ashr_i32 s17, s16, 31
	v_pk_add_f32 v[0:1], v[70:71], v[0:1]
	v_pk_mul_f32 v[66:67], v[22:23], v[66:67]
	v_add_f32_e32 v0, v0, v1
	v_pk_mul_f32 v[64:65], v[20:21], v[64:65]
	v_pk_mul_f32 v[62:63], v[30:31], v[62:63]
	v_pk_mul_f32 v[60:61], v[28:29], v[60:61]
	v_pk_mul_f32 v[58:59], v[26:27], v[58:59]
	v_pk_mul_f32 v[56:57], v[24:25], v[56:57]
	v_pk_mul_f32 v[54:55], v[34:35], v[54:55]
	v_pk_mul_f32 v[52:53], v[32:33], v[52:53]
	s_lshl_b64 s[2:3], s[16:17], 11
	s_nop 1
	v_add_f32_dpp v0, v0, v0 quad_perm:[1,0,3,2] row_mask:0xf bank_mask:0xf
	s_nop 1
	v_add_f32_dpp v0, v0, v0 quad_perm:[2,3,0,1] row_mask:0xf bank_mask:0xf
	s_nop 1
	v_add_f32_dpp v0, v0, v0 row_half_mirror row_mask:0xf bank_mask:0xf
	s_nop 1
	v_add_f32_dpp v0, v0, v0 row_mirror row_mask:0xf bank_mask:0xf
	s_nop 1
	v_add_f32_dpp v0, v0, v0 row_bcast:15 row_mask:0xa bank_mask:0xf
	s_nop 1
	v_add_f32_dpp v0, v0, v0 row_bcast:31 row_mask:0xc bank_mask:0xf
	s_nop 0
	v_readlane_b32 s32, v0, 63
	s_nop 1
	v_mov_b32_e32 v0, s32
	s_waitcnt lgkmcnt(0)
	v_fmamk_f32 v0, v0, 0x3a800000, v228
	v_mul_f32_e32 v1, 0x4b800000, v0
	v_cmp_gt_f32_e32 vcc, s37, v0
	s_nop 1
	v_cndmask_b32_e32 v0, v0, v1, vcc
	v_rsq_f32_e32 v0, v0
	s_nop 0
	v_mul_f32_e32 v1, 0x45800000, v0
	v_cndmask_b32_e32 v0, v0, v1, vcc
	v_pk_fma_f32 v[66:67], v[66:67], v[0:1], v[6:7] op_sel_hi:[1,0,1]
	v_pk_fma_f32 v[64:65], v[64:65], v[0:1], v[4:5] op_sel_hi:[1,0,1]
	v_pk_fma_f32 v[62:63], v[62:63], v[0:1], v[14:15] op_sel_hi:[1,0,1]
	v_pk_fma_f32 v[60:61], v[60:61], v[0:1], v[12:13] op_sel_hi:[1,0,1]
	v_pk_fma_f32 v[58:59], v[58:59], v[0:1], v[10:11] op_sel_hi:[1,0,1]
	v_pk_fma_f32 v[56:57], v[56:57], v[0:1], v[8:9] op_sel_hi:[1,0,1]
	v_pk_fma_f32 v[54:55], v[54:55], v[0:1], v[18:19] op_sel_hi:[1,0,1]
	v_pk_fma_f32 v[0:1], v[52:53], v[0:1], v[16:17] op_sel_hi:[1,0,1]
	v_cvt_pk_bf16_f32 v64, v64, v65
	v_cvt_pk_bf16_f32 v65, v66, v67
	v_lshl_add_u64 v[66:67], v[188:189], 0, s[2:3]
	v_cvt_pk_bf16_f32 v60, v60, v61
	v_cvt_pk_bf16_f32 v61, v62, v63
	v_cvt_pk_bf16_f32 v56, v56, v57
	v_cvt_pk_bf16_f32 v57, v58, v59
	v_cvt_pk_bf16_f32 v0, v0, v1
	v_cvt_pk_bf16_f32 v1, v54, v55
	global_store_dwordx2 v[66:67], v[64:65], off
	global_store_dwordx2 v[66:67], v[60:61], off offset:512
	global_store_dwordx2 v[66:67], v[56:57], off offset:1024
	global_store_dwordx2 v[66:67], v[0:1], off offset:1536
	s_branch .LBB0_742
